# prep MOD mat-vec: all 64 weight loads of a unit issued up front, k-loop unrolled 4x
# speedup vs baseline: 1.0067x; 1.0067x over previous
.LBB0_155:
	v_lshl_add_u64 v[18:19], v[60:61], 0, s[20:21]
	v_add_co_u32_e64 v20, s[0:1], s29, v18
	s_nop 1
	v_addc_co_u32_e64 v21, s[0:1], 0, v19, s[0:1]
	v_add_co_u32_e64 v26, s[0:1], s5, v18
	s_add_u32 s20, s20, 0x30000
	s_nop 1
	v_addc_co_u32_e64 v27, s[0:1], 0, v19, s[0:1]
	s_mov_b32 s0, 0x9000
	v_add_co_u32_e64 v46, s[0:1], s0, v18
	s_nop 1
	global_load_dword v108, v[18:19], off
	s_nop 1
	global_load_dword v109, v[20:21], off
	s_nop 1
	global_load_dword v110, v[26:27], off
	s_nop 1
	v_addc_co_u32_e64 v47, s[0:1], 0, v19, s[0:1]
	v_add_co_u32_e64 v48, s[0:1], s50, v18
	s_nop 1
	v_addc_co_u32_e64 v49, s[0:1], 0, v19, s[0:1]
	s_mov_b32 s0, 0xf000
	v_add_co_u32_e64 v76, s[0:1], s0, v18
	s_addc_u32 s21, s21, 0
	s_nop 1
	v_addc_co_u32_e64 v77, s[0:1], 0, v19, s[0:1]
	s_mov_b32 s0, 0x12000
	v_add_co_u32_e64 v78, s[0:1], s0, v18
	s_nop 1
	v_addc_co_u32_e64 v79, s[0:1], 0, v19, s[0:1]
	s_nop 1
	global_load_dword v111, v[46:47], off
	s_nop 1
	global_load_dword v112, v[48:49], off
	s_nop 1
	global_load_dword v113, v[76:77], off
	s_nop 1
	global_load_dword v114, v[78:79], off
	s_mov_b32 s0, 0x15000
	v_add_co_u32_e64 v80, s[0:1], s0, v18
	s_nop 1
	v_addc_co_u32_e64 v81, s[0:1], 0, v19, s[0:1]
	v_add_co_u32_e64 v30, s[0:1], s96, v18
	s_nop 1
	global_load_dword v115, v[80:81], off
	s_nop 1
	v_addc_co_u32_e64 v31, s[0:1], 0, v19, s[0:1]
	s_mov_b32 s0, 0x1b000
	v_add_co_u32_e64 v34, s[0:1], s0, v18
	s_nop 1
	v_addc_co_u32_e64 v35, s[0:1], 0, v19, s[0:1]
	s_mov_b32 s0, 0x1e000
	v_add_co_u32_e64 v40, s[0:1], s0, v18
	s_nop 1
	v_addc_co_u32_e64 v41, s[0:1], 0, v19, s[0:1]
	s_mov_b32 s0, 0x21000
	v_add_co_u32_e64 v32, s[0:1], s0, v18
	s_nop 1
	v_addc_co_u32_e64 v33, s[0:1], 0, v19, s[0:1]
	s_mov_b32 s0, 0x24000
	v_add_co_u32_e64 v38, s[0:1], s0, v18
	s_nop 1
	v_addc_co_u32_e64 v39, s[0:1], 0, v19, s[0:1]
	s_mov_b32 s0, 0x27000
	v_add_co_u32_e64 v42, s[0:1], s0, v18
	s_nop 1
	v_addc_co_u32_e64 v43, s[0:1], 0, v19, s[0:1]
	s_mov_b32 s0, 0x2a000
	v_add_co_u32_e64 v44, s[0:1], s0, v18
	s_nop 1
	v_addc_co_u32_e64 v45, s[0:1], 0, v19, s[0:1]
	s_mov_b32 s0, 0x2d000
	v_add_co_u32_e64 v36, s[0:1], s0, v18
	s_nop 1
	v_addc_co_u32_e64 v37, s[0:1], 0, v19, s[0:1]
	s_nop 1
	global_load_dword v116, v[30:31], off
	s_nop 1
	global_load_dword v117, v[34:35], off
	s_nop 1
	global_load_dword v118, v[40:41], off
	s_nop 1
	global_load_dword v119, v[32:33], off
	s_nop 1
	global_load_dword v120, v[38:39], off
	s_nop 1
	global_load_dword v121, v[42:43], off
	s_nop 1
	global_load_dword v122, v[44:45], off
	s_nop 1
	global_load_dword v123, v[36:37], off
	v_lshl_add_u64 v[18:19], v[60:61], 0, s[20:21]
	v_add_co_u32_e64 v20, s[0:1], s29, v18
	s_nop 1
	v_addc_co_u32_e64 v21, s[0:1], 0, v19, s[0:1]
	v_add_co_u32_e64 v26, s[0:1], s5, v18
	s_add_u32 s20, s20, 0x30000
	s_nop 1
	v_addc_co_u32_e64 v27, s[0:1], 0, v19, s[0:1]
	s_mov_b32 s0, 0x9000
	v_add_co_u32_e64 v46, s[0:1], s0, v18
	s_nop 1
	global_load_dword v124, v[18:19], off
	s_nop 1
	global_load_dword v125, v[20:21], off
	s_nop 1
	global_load_dword v126, v[26:27], off
	s_nop 1
	v_addc_co_u32_e64 v47, s[0:1], 0, v19, s[0:1]
	v_add_co_u32_e64 v48, s[0:1], s50, v18
	s_nop 1
	v_addc_co_u32_e64 v49, s[0:1], 0, v19, s[0:1]
	s_mov_b32 s0, 0xf000
	v_add_co_u32_e64 v76, s[0:1], s0, v18
	s_addc_u32 s21, s21, 0
	s_nop 1
	v_addc_co_u32_e64 v77, s[0:1], 0, v19, s[0:1]
	s_mov_b32 s0, 0x12000
	v_add_co_u32_e64 v78, s[0:1], s0, v18
	s_nop 1
	v_addc_co_u32_e64 v79, s[0:1], 0, v19, s[0:1]
	s_nop 1
	global_load_dword v127, v[46:47], off
	s_nop 1
	global_load_dword v128, v[48:49], off
	s_nop 1
	global_load_dword v129, v[76:77], off
	s_nop 1
	global_load_dword v130, v[78:79], off
	s_mov_b32 s0, 0x15000
	v_add_co_u32_e64 v80, s[0:1], s0, v18
	s_nop 1
	v_addc_co_u32_e64 v81, s[0:1], 0, v19, s[0:1]
	v_add_co_u32_e64 v30, s[0:1], s96, v18
	s_nop 1
	global_load_dword v131, v[80:81], off
	s_nop 1
	v_addc_co_u32_e64 v31, s[0:1], 0, v19, s[0:1]
	s_mov_b32 s0, 0x1b000
	v_add_co_u32_e64 v34, s[0:1], s0, v18
	s_nop 1
	v_addc_co_u32_e64 v35, s[0:1], 0, v19, s[0:1]
	s_mov_b32 s0, 0x1e000
	v_add_co_u32_e64 v40, s[0:1], s0, v18
	s_nop 1
	v_addc_co_u32_e64 v41, s[0:1], 0, v19, s[0:1]
	s_mov_b32 s0, 0x21000
	v_add_co_u32_e64 v32, s[0:1], s0, v18
	s_nop 1
	v_addc_co_u32_e64 v33, s[0:1], 0, v19, s[0:1]
	s_mov_b32 s0, 0x24000
	v_add_co_u32_e64 v38, s[0:1], s0, v18
	s_nop 1
	v_addc_co_u32_e64 v39, s[0:1], 0, v19, s[0:1]
	s_mov_b32 s0, 0x27000
	v_add_co_u32_e64 v42, s[0:1], s0, v18
	s_nop 1
	v_addc_co_u32_e64 v43, s[0:1], 0, v19, s[0:1]
	s_mov_b32 s0, 0x2a000
	v_add_co_u32_e64 v44, s[0:1], s0, v18
	s_nop 1
	v_addc_co_u32_e64 v45, s[0:1], 0, v19, s[0:1]
	s_mov_b32 s0, 0x2d000
	v_add_co_u32_e64 v36, s[0:1], s0, v18
	s_nop 1
	v_addc_co_u32_e64 v37, s[0:1], 0, v19, s[0:1]
	s_nop 1
	global_load_dword v132, v[30:31], off
	s_nop 1
	global_load_dword v133, v[34:35], off
	s_nop 1
	global_load_dword v134, v[40:41], off
	s_nop 1
	global_load_dword v135, v[32:33], off
	s_nop 1
	global_load_dword v136, v[38:39], off
	s_nop 1
	global_load_dword v137, v[42:43], off
	s_nop 1
	global_load_dword v138, v[44:45], off
	s_nop 1
	global_load_dword v139, v[36:37], off
	v_lshl_add_u64 v[18:19], v[60:61], 0, s[20:21]
	v_add_co_u32_e64 v20, s[0:1], s29, v18
	s_nop 1
	v_addc_co_u32_e64 v21, s[0:1], 0, v19, s[0:1]
	v_add_co_u32_e64 v26, s[0:1], s5, v18
	s_add_u32 s20, s20, 0x30000
	s_nop 1
	v_addc_co_u32_e64 v27, s[0:1], 0, v19, s[0:1]
	s_mov_b32 s0, 0x9000
	v_add_co_u32_e64 v46, s[0:1], s0, v18
	s_nop 1
	global_load_dword v140, v[18:19], off
	s_nop 1
	global_load_dword v141, v[20:21], off
	s_nop 1
	global_load_dword v142, v[26:27], off
	s_nop 1
	v_addc_co_u32_e64 v47, s[0:1], 0, v19, s[0:1]
	v_add_co_u32_e64 v48, s[0:1], s50, v18
	s_nop 1
	v_addc_co_u32_e64 v49, s[0:1], 0, v19, s[0:1]
	s_mov_b32 s0, 0xf000
	v_add_co_u32_e64 v76, s[0:1], s0, v18
	s_addc_u32 s21, s21, 0
	s_nop 1
	v_addc_co_u32_e64 v77, s[0:1], 0, v19, s[0:1]
	s_mov_b32 s0, 0x12000
	v_add_co_u32_e64 v78, s[0:1], s0, v18
	s_nop 1
	v_addc_co_u32_e64 v79, s[0:1], 0, v19, s[0:1]
	s_nop 1
	global_load_dword v143, v[46:47], off
	s_nop 1
	global_load_dword v144, v[48:49], off
	s_nop 1
	global_load_dword v145, v[76:77], off
	s_nop 1
	global_load_dword v146, v[78:79], off
	s_mov_b32 s0, 0x15000
	v_add_co_u32_e64 v80, s[0:1], s0, v18
	s_nop 1
	v_addc_co_u32_e64 v81, s[0:1], 0, v19, s[0:1]
	v_add_co_u32_e64 v30, s[0:1], s96, v18
	s_nop 1
	global_load_dword v147, v[80:81], off
	s_nop 1
	v_addc_co_u32_e64 v31, s[0:1], 0, v19, s[0:1]
	s_mov_b32 s0, 0x1b000
	v_add_co_u32_e64 v34, s[0:1], s0, v18
	s_nop 1
	v_addc_co_u32_e64 v35, s[0:1], 0, v19, s[0:1]
	s_mov_b32 s0, 0x1e000
	v_add_co_u32_e64 v40, s[0:1], s0, v18
	s_nop 1
	v_addc_co_u32_e64 v41, s[0:1], 0, v19, s[0:1]
	s_mov_b32 s0, 0x21000
	v_add_co_u32_e64 v32, s[0:1], s0, v18
	s_nop 1
	v_addc_co_u32_e64 v33, s[0:1], 0, v19, s[0:1]
	s_mov_b32 s0, 0x24000
	v_add_co_u32_e64 v38, s[0:1], s0, v18
	s_nop 1
	v_addc_co_u32_e64 v39, s[0:1], 0, v19, s[0:1]
	s_mov_b32 s0, 0x27000
	v_add_co_u32_e64 v42, s[0:1], s0, v18
	s_nop 1
	v_addc_co_u32_e64 v43, s[0:1], 0, v19, s[0:1]
	s_mov_b32 s0, 0x2a000
	v_add_co_u32_e64 v44, s[0:1], s0, v18
	s_nop 1
	v_addc_co_u32_e64 v45, s[0:1], 0, v19, s[0:1]
	s_mov_b32 s0, 0x2d000
	v_add_co_u32_e64 v36, s[0:1], s0, v18
	s_nop 1
	v_addc_co_u32_e64 v37, s[0:1], 0, v19, s[0:1]
	s_nop 1
	global_load_dword v148, v[30:31], off
	s_nop 1
	global_load_dword v149, v[34:35], off
	s_nop 1
	global_load_dword v150, v[40:41], off
	s_nop 1
	global_load_dword v151, v[32:33], off
	s_nop 1
	global_load_dword v152, v[38:39], off
	s_nop 1
	global_load_dword v153, v[42:43], off
	s_nop 1
	global_load_dword v154, v[44:45], off
	s_nop 1
	global_load_dword v155, v[36:37], off
	v_lshl_add_u64 v[18:19], v[60:61], 0, s[20:21]
	v_add_co_u32_e64 v20, s[0:1], s29, v18
	s_nop 1
	v_addc_co_u32_e64 v21, s[0:1], 0, v19, s[0:1]
	v_add_co_u32_e64 v26, s[0:1], s5, v18
	s_add_u32 s20, s20, 0x30000
	s_nop 1
	v_addc_co_u32_e64 v27, s[0:1], 0, v19, s[0:1]
	s_mov_b32 s0, 0x9000
	v_add_co_u32_e64 v46, s[0:1], s0, v18
	s_nop 1
	global_load_dword v156, v[18:19], off
	s_nop 1
	global_load_dword v157, v[20:21], off
	s_nop 1
	global_load_dword v158, v[26:27], off
	s_nop 1
	v_addc_co_u32_e64 v47, s[0:1], 0, v19, s[0:1]
	v_add_co_u32_e64 v48, s[0:1], s50, v18
	s_nop 1
	v_addc_co_u32_e64 v49, s[0:1], 0, v19, s[0:1]
	s_mov_b32 s0, 0xf000
	v_add_co_u32_e64 v76, s[0:1], s0, v18
	s_addc_u32 s21, s21, 0
	s_nop 1
	v_addc_co_u32_e64 v77, s[0:1], 0, v19, s[0:1]
	s_mov_b32 s0, 0x12000
	v_add_co_u32_e64 v78, s[0:1], s0, v18
	s_nop 1
	v_addc_co_u32_e64 v79, s[0:1], 0, v19, s[0:1]
	s_nop 1
	global_load_dword v159, v[46:47], off
	s_nop 1
	global_load_dword v160, v[48:49], off
	s_nop 1
	global_load_dword v161, v[76:77], off
	s_nop 1
	global_load_dword v162, v[78:79], off
	s_mov_b32 s0, 0x15000
	v_add_co_u32_e64 v80, s[0:1], s0, v18
	s_nop 1
	v_addc_co_u32_e64 v81, s[0:1], 0, v19, s[0:1]
	v_add_co_u32_e64 v30, s[0:1], s96, v18
	s_nop 1
	global_load_dword v163, v[80:81], off
	s_nop 1
	v_addc_co_u32_e64 v31, s[0:1], 0, v19, s[0:1]
	s_mov_b32 s0, 0x1b000
	v_add_co_u32_e64 v34, s[0:1], s0, v18
	s_nop 1
	v_addc_co_u32_e64 v35, s[0:1], 0, v19, s[0:1]
	s_mov_b32 s0, 0x1e000
	v_add_co_u32_e64 v40, s[0:1], s0, v18
	s_nop 1
	v_addc_co_u32_e64 v41, s[0:1], 0, v19, s[0:1]
	s_mov_b32 s0, 0x21000
	v_add_co_u32_e64 v32, s[0:1], s0, v18
	s_nop 1
	v_addc_co_u32_e64 v33, s[0:1], 0, v19, s[0:1]
	s_mov_b32 s0, 0x24000
	v_add_co_u32_e64 v38, s[0:1], s0, v18
	s_nop 1
	v_addc_co_u32_e64 v39, s[0:1], 0, v19, s[0:1]
	s_mov_b32 s0, 0x27000
	v_add_co_u32_e64 v42, s[0:1], s0, v18
	s_nop 1
	v_addc_co_u32_e64 v43, s[0:1], 0, v19, s[0:1]
	s_mov_b32 s0, 0x2a000
	v_add_co_u32_e64 v44, s[0:1], s0, v18
	s_nop 1
	v_addc_co_u32_e64 v45, s[0:1], 0, v19, s[0:1]
	s_mov_b32 s0, 0x2d000
	v_add_co_u32_e64 v36, s[0:1], s0, v18
	s_nop 1
	v_addc_co_u32_e64 v37, s[0:1], 0, v19, s[0:1]
	s_nop 1
	global_load_dword v164, v[30:31], off
	s_nop 1
	global_load_dword v165, v[34:35], off
	s_nop 1
	global_load_dword v166, v[40:41], off
	s_nop 1
	global_load_dword v167, v[32:33], off
	s_nop 1
	global_load_dword v168, v[38:39], off
	s_nop 1
	global_load_dword v169, v[42:43], off
	s_nop 1
	global_load_dword v170, v[44:45], off
	s_nop 1
	global_load_dword v171, v[36:37], off
	s_mov_b64 s[20:21], 0
	s_waitcnt vmcnt(0)
	v_lshl_add_u64 v[18:19], v[60:61], 0, s[20:21]
	v_add_co_u32_e64 v20, s[0:1], s29, v18
	ds_read_b128 v[72:75], v64
	ds_read_b128 v[6:9], v64 offset:16
	ds_read_b128 v[22:25], v64 offset:4096
	ds_read_b128 v[14:17], v64 offset:8192
	ds_read_b128 v[10:13], v64 offset:12288
	ds_read_b128 v[2:5], v64 offset:16384
	v_addc_co_u32_e64 v21, s[0:1], 0, v19, s[0:1]
	v_add_co_u32_e64 v26, s[0:1], s5, v18
	s_add_u32 s20, s20, 0x30000
	s_nop 0
	v_addc_co_u32_e64 v27, s[0:1], 0, v19, s[0:1]
	s_mov_b32 s0, 0x9000
	s_nop 0
	v_add_co_u32_e64 v46, s[0:1], s0, v18
	v_mov_b32_e32 v50, v108
	v_mov_b32_e32 v51, v109
	v_mov_b32_e32 v52, v110
	v_addc_co_u32_e64 v47, s[0:1], 0, v19, s[0:1]
	v_add_co_u32_e64 v48, s[0:1], s50, v18
	ds_read_b128 v[26:29], v64 offset:20480
	s_nop 0
	v_addc_co_u32_e64 v49, s[0:1], 0, v19, s[0:1]
	s_mov_b32 s0, 0xf000
	s_nop 0
	v_add_co_u32_e64 v76, s[0:1], s0, v18
	s_addc_u32 s21, s21, 0
	s_nop 0
	v_addc_co_u32_e64 v77, s[0:1], 0, v19, s[0:1]
	s_mov_b32 s0, 0x12000
	s_nop 0
	v_add_co_u32_e64 v78, s[0:1], s0, v18
	s_cmp_eq_u32 s20, 0xc0000
	s_nop 0
	v_addc_co_u32_e64 v79, s[0:1], 0, v19, s[0:1]
	v_mov_b32_e32 v53, v111
	s_nop 0
	v_mov_b32_e32 v49, v112
	s_nop 0
	v_mov_b32_e32 v48, v113
	v_mov_b32_e32 v47, v114
	s_mov_b32 s0, 0x15000
	v_add_co_u32_e64 v80, s[0:1], s0, v18
	ds_read_b128 v[82:85], v64 offset:12304
	ds_read_b128 v[86:89], v64 offset:16400
	v_addc_co_u32_e64 v81, s[0:1], 0, v19, s[0:1]
	v_add_co_u32_e64 v30, s[0:1], s96, v18
	v_mov_b32_e32 v46, v115
	s_nop 0
	v_addc_co_u32_e64 v31, s[0:1], 0, v19, s[0:1]
	s_mov_b32 s0, 0x1b000
	s_nop 0
	v_add_co_u32_e64 v34, s[0:1], s0, v18
	ds_read_b128 v[78:81], v64 offset:4112
	s_nop 0
	v_addc_co_u32_e64 v35, s[0:1], 0, v19, s[0:1]
	s_mov_b32 s0, 0x1e000
	s_nop 0
	v_add_co_u32_e64 v40, s[0:1], s0, v18
	ds_read_b128 v[90:93], v64 offset:20496
	s_nop 0
	v_addc_co_u32_e64 v41, s[0:1], 0, v19, s[0:1]
	s_mov_b32 s0, 0x21000
	s_nop 0
	v_add_co_u32_e64 v32, s[0:1], s0, v18
	ds_read_b128 v[94:97], v64 offset:24592
	s_nop 0
	v_addc_co_u32_e64 v33, s[0:1], 0, v19, s[0:1]
	s_mov_b32 s0, 0x24000
	s_nop 0
	v_add_co_u32_e64 v38, s[0:1], s0, v18
	s_waitcnt lgkmcnt(9)
	v_fmac_f32_e32 v65, v50, v22
	v_addc_co_u32_e64 v39, s[0:1], 0, v19, s[0:1]
	s_mov_b32 s0, 0x27000
	s_nop 0
	v_add_co_u32_e64 v42, s[0:1], s0, v18
	s_waitcnt lgkmcnt(6)
	v_fmac_f32_e32 v68, v50, v2
	v_addc_co_u32_e64 v43, s[0:1], 0, v19, s[0:1]
	s_mov_b32 s0, 0x2a000
	s_nop 0
	v_add_co_u32_e64 v44, s[0:1], s0, v18
	v_fmac_f32_e32 v65, v51, v23
	v_addc_co_u32_e64 v45, s[0:1], 0, v19, s[0:1]
	s_mov_b32 s0, 0x2d000
	s_nop 0
	v_add_co_u32_e64 v36, s[0:1], s0, v18
	v_fmac_f32_e32 v68, v51, v3
	s_nop 0
	v_addc_co_u32_e64 v37, s[0:1], 0, v19, s[0:1]
	ds_read_b128 v[18:21], v64 offset:24576
	v_fmac_f32_e32 v65, v52, v24
	v_fmac_f32_e32 v68, v52, v4
	v_fmac_f32_e32 v65, v53, v25
	ds_read_b128 v[22:25], v64 offset:8208
	v_fmac_f32_e32 v68, v53, v5
	ds_read_b128 v[2:5], v64 offset:28672
	ds_read_b128 v[98:101], v64 offset:28688
	v_fmac_f32_e32 v0, v50, v72
	v_fmac_f32_e32 v66, v50, v14
	v_fmac_f32_e32 v67, v50, v10
	s_waitcnt lgkmcnt(9)
	v_fmac_f32_e32 v69, v50, v26
	s_waitcnt lgkmcnt(3)
	v_fmac_f32_e32 v70, v50, v18
	s_waitcnt lgkmcnt(1)
	v_fmac_f32_e32 v71, v50, v2
	v_fmac_f32_e32 v0, v51, v73
	v_fmac_f32_e32 v66, v51, v15
	v_fmac_f32_e32 v67, v51, v11
	v_fmac_f32_e32 v69, v51, v27
	v_fmac_f32_e32 v70, v51, v19
	v_fmac_f32_e32 v71, v51, v3
	v_fmac_f32_e32 v0, v52, v74
	v_fmac_f32_e32 v66, v52, v16
	v_fmac_f32_e32 v67, v52, v12
	v_fmac_f32_e32 v69, v52, v28
	v_fmac_f32_e32 v70, v52, v20
	v_fmac_f32_e32 v71, v52, v4
	v_fmac_f32_e32 v0, v53, v75
	v_fmac_f32_e32 v66, v53, v17
	v_fmac_f32_e32 v67, v53, v13
	v_fmac_f32_e32 v69, v53, v29
	v_fmac_f32_e32 v70, v53, v21
	v_fmac_f32_e32 v71, v53, v5
	ds_read_b128 v[50:53], v64 offset:32
	v_mov_b32_e32 v77, v116
	v_mov_b32_e32 v106, v117
	v_mov_b32_e32 v107, v118
	ds_read_b128 v[2:5], v64 offset:48
	v_mov_b32_e32 v76, v119
	v_mov_b32_e32 v75, v120
	v_mov_b32_e32 v74, v121
	v_mov_b32_e32 v72, v122
	v_mov_b32_e32 v73, v123
	ds_read_b128 v[42:45], v64 offset:4128
	ds_read_b128 v[26:29], v64 offset:4144
	v_fmac_f32_e32 v0, v49, v6
	v_fmac_f32_e32 v65, v49, v78
	v_fmac_f32_e32 v66, v49, v22
	v_fmac_f32_e32 v0, v48, v7
	v_fmac_f32_e32 v65, v48, v79
	v_fmac_f32_e32 v66, v48, v23
	v_fmac_f32_e32 v0, v47, v8
	v_fmac_f32_e32 v65, v47, v80
	v_fmac_f32_e32 v66, v47, v24
	ds_read_b128 v[102:105], v64 offset:8224
	ds_read_b128 v[30:33], v64 offset:8240
	v_fmac_f32_e32 v0, v46, v9
	ds_read_b128 v[6:9], v64 offset:12320
	ds_read_b128 v[34:37], v64 offset:12336
	v_fmac_f32_e32 v65, v46, v81
	ds_read_b128 v[10:13], v64 offset:16416
	ds_read_b128 v[38:41], v64 offset:16432
	v_fmac_f32_e32 v66, v46, v25
	ds_read_b128 v[14:17], v64 offset:20512
	ds_read_b128 v[18:21], v64 offset:24608
	ds_read_b128 v[22:25], v64 offset:28704
	v_fmac_f32_e32 v67, v49, v82
	v_fmac_f32_e32 v68, v49, v86
	v_fmac_f32_e32 v69, v49, v90
	v_fmac_f32_e32 v70, v49, v94
	s_waitcnt lgkmcnt(13)
	v_fmac_f32_e32 v71, v49, v98
	v_fmac_f32_e32 v67, v48, v83
	v_fmac_f32_e32 v68, v48, v87
	v_fmac_f32_e32 v69, v48, v91
	v_fmac_f32_e32 v70, v48, v95
	v_fmac_f32_e32 v71, v48, v99
	v_fmac_f32_e32 v67, v47, v84
	v_fmac_f32_e32 v68, v47, v88
	v_fmac_f32_e32 v69, v47, v92
	v_fmac_f32_e32 v70, v47, v96
	v_fmac_f32_e32 v71, v47, v100
	v_fmac_f32_e32 v67, v46, v85
	v_fmac_f32_e32 v68, v46, v89
	v_fmac_f32_e32 v69, v46, v93
	v_fmac_f32_e32 v70, v46, v97
	v_fmac_f32_e32 v71, v46, v101
	ds_read_b128 v[46:49], v64 offset:24624
	s_waitcnt lgkmcnt(13)
	v_fmac_f32_e32 v0, v77, v50
	s_waitcnt lgkmcnt(11)
	v_fmac_f32_e32 v65, v77, v42
	v_fmac_f32_e32 v0, v106, v51
	v_fmac_f32_e32 v65, v106, v43
	v_fmac_f32_e32 v0, v107, v52
	v_fmac_f32_e32 v65, v107, v44
	v_fmac_f32_e32 v0, v76, v53
	v_fmac_f32_e32 v65, v76, v45
	ds_read_b128 v[42:45], v64 offset:20528
	ds_read_b128 v[50:53], v64 offset:28720
	s_waitcnt lgkmcnt(11)
	v_fmac_f32_e32 v66, v77, v102
	s_waitcnt lgkmcnt(9)
	v_fmac_f32_e32 v67, v77, v6
	s_waitcnt lgkmcnt(7)
	v_fmac_f32_e32 v68, v77, v10
	s_waitcnt lgkmcnt(5)
	v_fmac_f32_e32 v69, v77, v14
	s_waitcnt lgkmcnt(4)
	v_fmac_f32_e32 v70, v77, v18
	s_waitcnt lgkmcnt(3)
	v_fmac_f32_e32 v71, v77, v22
	v_fmac_f32_e32 v66, v106, v103
	v_fmac_f32_e32 v67, v106, v7
	v_fmac_f32_e32 v68, v106, v11
	v_fmac_f32_e32 v69, v106, v15
	v_fmac_f32_e32 v70, v106, v19
	v_fmac_f32_e32 v71, v106, v23
	v_fmac_f32_e32 v66, v107, v104
	v_fmac_f32_e32 v67, v107, v8
	v_fmac_f32_e32 v68, v107, v12
	v_fmac_f32_e32 v69, v107, v16
	v_fmac_f32_e32 v70, v107, v20
	v_fmac_f32_e32 v71, v107, v24
	v_fmac_f32_e32 v66, v76, v105
	v_fmac_f32_e32 v67, v76, v9
	v_fmac_f32_e32 v68, v76, v13
	v_fmac_f32_e32 v69, v76, v17
	v_fmac_f32_e32 v70, v76, v21
	v_fmac_f32_e32 v71, v76, v25
	v_fmac_f32_e32 v0, v75, v2
	v_fmac_f32_e32 v65, v75, v26
	v_fmac_f32_e32 v66, v75, v30
	v_fmac_f32_e32 v67, v75, v34
	v_fmac_f32_e32 v68, v75, v38
	s_waitcnt lgkmcnt(1)
	v_fmac_f32_e32 v69, v75, v42
	v_fmac_f32_e32 v70, v75, v46
	s_waitcnt lgkmcnt(0)
	v_fmac_f32_e32 v71, v75, v50
	v_fmac_f32_e32 v0, v74, v3
	v_fmac_f32_e32 v65, v74, v27
	v_fmac_f32_e32 v66, v74, v31
	v_fmac_f32_e32 v67, v74, v35
	v_fmac_f32_e32 v68, v74, v39
	v_fmac_f32_e32 v69, v74, v43
	v_fmac_f32_e32 v70, v74, v47
	v_fmac_f32_e32 v71, v74, v51
	v_fmac_f32_e32 v0, v72, v4
	v_fmac_f32_e32 v65, v72, v28
	v_fmac_f32_e32 v66, v72, v32
	v_fmac_f32_e32 v67, v72, v36
	v_fmac_f32_e32 v68, v72, v40
	v_fmac_f32_e32 v69, v72, v44
	v_fmac_f32_e32 v70, v72, v48
	v_fmac_f32_e32 v71, v72, v52
	v_add_u32_e32 v64, 64, v64
	v_fmac_f32_e32 v0, v73, v5
	v_fmac_f32_e32 v65, v73, v29
	v_fmac_f32_e32 v66, v73, v33
	v_fmac_f32_e32 v67, v73, v37
	v_fmac_f32_e32 v68, v73, v41
	v_fmac_f32_e32 v69, v73, v45
	v_fmac_f32_e32 v70, v73, v49
	v_fmac_f32_e32 v71, v73, v53
	v_lshl_add_u64 v[18:19], v[60:61], 0, s[20:21]
	v_add_co_u32_e64 v20, s[0:1], s29, v18
	ds_read_b128 v[72:75], v64
	ds_read_b128 v[6:9], v64 offset:16
	ds_read_b128 v[22:25], v64 offset:4096
	ds_read_b128 v[14:17], v64 offset:8192
	ds_read_b128 v[10:13], v64 offset:12288
	ds_read_b128 v[2:5], v64 offset:16384
	v_addc_co_u32_e64 v21, s[0:1], 0, v19, s[0:1]
	v_add_co_u32_e64 v26, s[0:1], s5, v18
	s_add_u32 s20, s20, 0x30000
	s_nop 0
	v_addc_co_u32_e64 v27, s[0:1], 0, v19, s[0:1]
	s_mov_b32 s0, 0x9000
	s_nop 0
	v_add_co_u32_e64 v46, s[0:1], s0, v18
	v_mov_b32_e32 v50, v124
	v_mov_b32_e32 v51, v125
	v_mov_b32_e32 v52, v126
	v_addc_co_u32_e64 v47, s[0:1], 0, v19, s[0:1]
	v_add_co_u32_e64 v48, s[0:1], s50, v18
	ds_read_b128 v[26:29], v64 offset:20480
	s_nop 0
	v_addc_co_u32_e64 v49, s[0:1], 0, v19, s[0:1]
	s_mov_b32 s0, 0xf000
	s_nop 0
	v_add_co_u32_e64 v76, s[0:1], s0, v18
	s_addc_u32 s21, s21, 0
	s_nop 0
	v_addc_co_u32_e64 v77, s[0:1], 0, v19, s[0:1]
	s_mov_b32 s0, 0x12000
	s_nop 0
	v_add_co_u32_e64 v78, s[0:1], s0, v18
	s_cmp_eq_u32 s20, 0xc0000
	s_nop 0
	v_addc_co_u32_e64 v79, s[0:1], 0, v19, s[0:1]
	v_mov_b32_e32 v53, v127
	s_nop 0
	v_mov_b32_e32 v49, v128
	s_nop 0
	v_mov_b32_e32 v48, v129
	v_mov_b32_e32 v47, v130
	s_mov_b32 s0, 0x15000
	v_add_co_u32_e64 v80, s[0:1], s0, v18
	ds_read_b128 v[82:85], v64 offset:12304
	ds_read_b128 v[86:89], v64 offset:16400
	v_addc_co_u32_e64 v81, s[0:1], 0, v19, s[0:1]
	v_add_co_u32_e64 v30, s[0:1], s96, v18
	v_mov_b32_e32 v46, v131
	s_nop 0
	v_addc_co_u32_e64 v31, s[0:1], 0, v19, s[0:1]
	s_mov_b32 s0, 0x1b000
	s_nop 0
	v_add_co_u32_e64 v34, s[0:1], s0, v18
	ds_read_b128 v[78:81], v64 offset:4112
	s_nop 0
	v_addc_co_u32_e64 v35, s[0:1], 0, v19, s[0:1]
	s_mov_b32 s0, 0x1e000
	s_nop 0
	v_add_co_u32_e64 v40, s[0:1], s0, v18
	ds_read_b128 v[90:93], v64 offset:20496
	s_nop 0
	v_addc_co_u32_e64 v41, s[0:1], 0, v19, s[0:1]
	s_mov_b32 s0, 0x21000
	s_nop 0
	v_add_co_u32_e64 v32, s[0:1], s0, v18
	ds_read_b128 v[94:97], v64 offset:24592
	s_nop 0
	v_addc_co_u32_e64 v33, s[0:1], 0, v19, s[0:1]
	s_mov_b32 s0, 0x24000
	s_nop 0
	v_add_co_u32_e64 v38, s[0:1], s0, v18
	s_waitcnt lgkmcnt(9)
	v_fmac_f32_e32 v65, v50, v22
	v_addc_co_u32_e64 v39, s[0:1], 0, v19, s[0:1]
	s_mov_b32 s0, 0x27000
	s_nop 0
	v_add_co_u32_e64 v42, s[0:1], s0, v18
	s_waitcnt lgkmcnt(6)
	v_fmac_f32_e32 v68, v50, v2
	v_addc_co_u32_e64 v43, s[0:1], 0, v19, s[0:1]
	s_mov_b32 s0, 0x2a000
	s_nop 0
	v_add_co_u32_e64 v44, s[0:1], s0, v18
	v_fmac_f32_e32 v65, v51, v23
	v_addc_co_u32_e64 v45, s[0:1], 0, v19, s[0:1]
	s_mov_b32 s0, 0x2d000
	s_nop 0
	v_add_co_u32_e64 v36, s[0:1], s0, v18
	v_fmac_f32_e32 v68, v51, v3
	s_nop 0
	v_addc_co_u32_e64 v37, s[0:1], 0, v19, s[0:1]
	ds_read_b128 v[18:21], v64 offset:24576
	v_fmac_f32_e32 v65, v52, v24
	v_fmac_f32_e32 v68, v52, v4
	v_fmac_f32_e32 v65, v53, v25
	ds_read_b128 v[22:25], v64 offset:8208
	v_fmac_f32_e32 v68, v53, v5
	ds_read_b128 v[2:5], v64 offset:28672
	ds_read_b128 v[98:101], v64 offset:28688
	v_fmac_f32_e32 v0, v50, v72
	v_fmac_f32_e32 v66, v50, v14
	v_fmac_f32_e32 v67, v50, v10
	s_waitcnt lgkmcnt(9)
	v_fmac_f32_e32 v69, v50, v26
	s_waitcnt lgkmcnt(3)
	v_fmac_f32_e32 v70, v50, v18
	s_waitcnt lgkmcnt(1)
	v_fmac_f32_e32 v71, v50, v2
	v_fmac_f32_e32 v0, v51, v73
	v_fmac_f32_e32 v66, v51, v15
	v_fmac_f32_e32 v67, v51, v11
	v_fmac_f32_e32 v69, v51, v27
	v_fmac_f32_e32 v70, v51, v19
	v_fmac_f32_e32 v71, v51, v3
	v_fmac_f32_e32 v0, v52, v74
	v_fmac_f32_e32 v66, v52, v16
	v_fmac_f32_e32 v67, v52, v12
	v_fmac_f32_e32 v69, v52, v28
	v_fmac_f32_e32 v70, v52, v20
	v_fmac_f32_e32 v71, v52, v4
	v_fmac_f32_e32 v0, v53, v75
	v_fmac_f32_e32 v66, v53, v17
	v_fmac_f32_e32 v67, v53, v13
	v_fmac_f32_e32 v69, v53, v29
	v_fmac_f32_e32 v70, v53, v21
	v_fmac_f32_e32 v71, v53, v5
	ds_read_b128 v[50:53], v64 offset:32
	v_mov_b32_e32 v77, v132
	v_mov_b32_e32 v106, v133
	v_mov_b32_e32 v107, v134
	ds_read_b128 v[2:5], v64 offset:48
	v_mov_b32_e32 v76, v135
	v_mov_b32_e32 v75, v136
	v_mov_b32_e32 v74, v137
	v_mov_b32_e32 v72, v138
	v_mov_b32_e32 v73, v139
	ds_read_b128 v[42:45], v64 offset:4128
	ds_read_b128 v[26:29], v64 offset:4144
	v_fmac_f32_e32 v0, v49, v6
	v_fmac_f32_e32 v65, v49, v78
	v_fmac_f32_e32 v66, v49, v22
	v_fmac_f32_e32 v0, v48, v7
	v_fmac_f32_e32 v65, v48, v79
	v_fmac_f32_e32 v66, v48, v23
	v_fmac_f32_e32 v0, v47, v8
	v_fmac_f32_e32 v65, v47, v80
	v_fmac_f32_e32 v66, v47, v24
	ds_read_b128 v[102:105], v64 offset:8224
	ds_read_b128 v[30:33], v64 offset:8240
	v_fmac_f32_e32 v0, v46, v9
	ds_read_b128 v[6:9], v64 offset:12320
	ds_read_b128 v[34:37], v64 offset:12336
	v_fmac_f32_e32 v65, v46, v81
	ds_read_b128 v[10:13], v64 offset:16416
	ds_read_b128 v[38:41], v64 offset:16432
	v_fmac_f32_e32 v66, v46, v25
	ds_read_b128 v[14:17], v64 offset:20512
	ds_read_b128 v[18:21], v64 offset:24608
	ds_read_b128 v[22:25], v64 offset:28704
	v_fmac_f32_e32 v67, v49, v82
	v_fmac_f32_e32 v68, v49, v86
	v_fmac_f32_e32 v69, v49, v90
	v_fmac_f32_e32 v70, v49, v94
	s_waitcnt lgkmcnt(13)
	v_fmac_f32_e32 v71, v49, v98
	v_fmac_f32_e32 v67, v48, v83
	v_fmac_f32_e32 v68, v48, v87
	v_fmac_f32_e32 v69, v48, v91
	v_fmac_f32_e32 v70, v48, v95
	v_fmac_f32_e32 v71, v48, v99
	v_fmac_f32_e32 v67, v47, v84
	v_fmac_f32_e32 v68, v47, v88
	v_fmac_f32_e32 v69, v47, v92
	v_fmac_f32_e32 v70, v47, v96
	v_fmac_f32_e32 v71, v47, v100
	v_fmac_f32_e32 v67, v46, v85
	v_fmac_f32_e32 v68, v46, v89
	v_fmac_f32_e32 v69, v46, v93
	v_fmac_f32_e32 v70, v46, v97
	v_fmac_f32_e32 v71, v46, v101
	ds_read_b128 v[46:49], v64 offset:24624
	s_waitcnt lgkmcnt(13)
	v_fmac_f32_e32 v0, v77, v50
	s_waitcnt lgkmcnt(11)
	v_fmac_f32_e32 v65, v77, v42
	v_fmac_f32_e32 v0, v106, v51
	v_fmac_f32_e32 v65, v106, v43
	v_fmac_f32_e32 v0, v107, v52
	v_fmac_f32_e32 v65, v107, v44
	v_fmac_f32_e32 v0, v76, v53
	v_fmac_f32_e32 v65, v76, v45
	ds_read_b128 v[42:45], v64 offset:20528
	ds_read_b128 v[50:53], v64 offset:28720
	s_waitcnt lgkmcnt(11)
	v_fmac_f32_e32 v66, v77, v102
	s_waitcnt lgkmcnt(9)
	v_fmac_f32_e32 v67, v77, v6
	s_waitcnt lgkmcnt(7)
	v_fmac_f32_e32 v68, v77, v10
	s_waitcnt lgkmcnt(5)
	v_fmac_f32_e32 v69, v77, v14
	s_waitcnt lgkmcnt(4)
	v_fmac_f32_e32 v70, v77, v18
	s_waitcnt lgkmcnt(3)
	v_fmac_f32_e32 v71, v77, v22
	v_fmac_f32_e32 v66, v106, v103
	v_fmac_f32_e32 v67, v106, v7
	v_fmac_f32_e32 v68, v106, v11
	v_fmac_f32_e32 v69, v106, v15
	v_fmac_f32_e32 v70, v106, v19
	v_fmac_f32_e32 v71, v106, v23
	v_fmac_f32_e32 v66, v107, v104
	v_fmac_f32_e32 v67, v107, v8
	v_fmac_f32_e32 v68, v107, v12
	v_fmac_f32_e32 v69, v107, v16
	v_fmac_f32_e32 v70, v107, v20
	v_fmac_f32_e32 v71, v107, v24
	v_fmac_f32_e32 v66, v76, v105
	v_fmac_f32_e32 v67, v76, v9
	v_fmac_f32_e32 v68, v76, v13
	v_fmac_f32_e32 v69, v76, v17
	v_fmac_f32_e32 v70, v76, v21
	v_fmac_f32_e32 v71, v76, v25
	v_fmac_f32_e32 v0, v75, v2
	v_fmac_f32_e32 v65, v75, v26
	v_fmac_f32_e32 v66, v75, v30
	v_fmac_f32_e32 v67, v75, v34
	v_fmac_f32_e32 v68, v75, v38
	s_waitcnt lgkmcnt(1)
	v_fmac_f32_e32 v69, v75, v42
	v_fmac_f32_e32 v70, v75, v46
	s_waitcnt lgkmcnt(0)
	v_fmac_f32_e32 v71, v75, v50
	v_fmac_f32_e32 v0, v74, v3
	v_fmac_f32_e32 v65, v74, v27
	v_fmac_f32_e32 v66, v74, v31
	v_fmac_f32_e32 v67, v74, v35
	v_fmac_f32_e32 v68, v74, v39
	v_fmac_f32_e32 v69, v74, v43
	v_fmac_f32_e32 v70, v74, v47
	v_fmac_f32_e32 v71, v74, v51
	v_fmac_f32_e32 v0, v72, v4
	v_fmac_f32_e32 v65, v72, v28
	v_fmac_f32_e32 v66, v72, v32
	v_fmac_f32_e32 v67, v72, v36
	v_fmac_f32_e32 v68, v72, v40
	v_fmac_f32_e32 v69, v72, v44
	v_fmac_f32_e32 v70, v72, v48
	v_fmac_f32_e32 v71, v72, v52
	v_add_u32_e32 v64, 64, v64
	v_fmac_f32_e32 v0, v73, v5
	v_fmac_f32_e32 v65, v73, v29
	v_fmac_f32_e32 v66, v73, v33
	v_fmac_f32_e32 v67, v73, v37
	v_fmac_f32_e32 v68, v73, v41
	v_fmac_f32_e32 v69, v73, v45
	v_fmac_f32_e32 v70, v73, v49
	v_fmac_f32_e32 v71, v73, v53
	v_lshl_add_u64 v[18:19], v[60:61], 0, s[20:21]
	v_add_co_u32_e64 v20, s[0:1], s29, v18
	ds_read_b128 v[72:75], v64
	ds_read_b128 v[6:9], v64 offset:16
	ds_read_b128 v[22:25], v64 offset:4096
	ds_read_b128 v[14:17], v64 offset:8192
	ds_read_b128 v[10:13], v64 offset:12288
	ds_read_b128 v[2:5], v64 offset:16384
	v_addc_co_u32_e64 v21, s[0:1], 0, v19, s[0:1]
	v_add_co_u32_e64 v26, s[0:1], s5, v18
	s_add_u32 s20, s20, 0x30000
	s_nop 0
	v_addc_co_u32_e64 v27, s[0:1], 0, v19, s[0:1]
	s_mov_b32 s0, 0x9000
	s_nop 0
	v_add_co_u32_e64 v46, s[0:1], s0, v18
	v_mov_b32_e32 v50, v140
	v_mov_b32_e32 v51, v141
	v_mov_b32_e32 v52, v142
	v_addc_co_u32_e64 v47, s[0:1], 0, v19, s[0:1]
	v_add_co_u32_e64 v48, s[0:1], s50, v18
	ds_read_b128 v[26:29], v64 offset:20480
	s_nop 0
	v_addc_co_u32_e64 v49, s[0:1], 0, v19, s[0:1]
	s_mov_b32 s0, 0xf000
	s_nop 0
	v_add_co_u32_e64 v76, s[0:1], s0, v18
	s_addc_u32 s21, s21, 0
	s_nop 0
	v_addc_co_u32_e64 v77, s[0:1], 0, v19, s[0:1]
	s_mov_b32 s0, 0x12000
	s_nop 0
	v_add_co_u32_e64 v78, s[0:1], s0, v18
	s_cmp_eq_u32 s20, 0xc0000
	s_nop 0
	v_addc_co_u32_e64 v79, s[0:1], 0, v19, s[0:1]
	v_mov_b32_e32 v53, v143
	s_nop 0
	v_mov_b32_e32 v49, v144
	s_nop 0
	v_mov_b32_e32 v48, v145
	v_mov_b32_e32 v47, v146
	s_mov_b32 s0, 0x15000
	v_add_co_u32_e64 v80, s[0:1], s0, v18
	ds_read_b128 v[82:85], v64 offset:12304
	ds_read_b128 v[86:89], v64 offset:16400
	v_addc_co_u32_e64 v81, s[0:1], 0, v19, s[0:1]
	v_add_co_u32_e64 v30, s[0:1], s96, v18
	v_mov_b32_e32 v46, v147
	s_nop 0
	v_addc_co_u32_e64 v31, s[0:1], 0, v19, s[0:1]
	s_mov_b32 s0, 0x1b000
	s_nop 0
	v_add_co_u32_e64 v34, s[0:1], s0, v18
	ds_read_b128 v[78:81], v64 offset:4112
	s_nop 0
	v_addc_co_u32_e64 v35, s[0:1], 0, v19, s[0:1]
	s_mov_b32 s0, 0x1e000
	s_nop 0
	v_add_co_u32_e64 v40, s[0:1], s0, v18
	ds_read_b128 v[90:93], v64 offset:20496
	s_nop 0
	v_addc_co_u32_e64 v41, s[0:1], 0, v19, s[0:1]
	s_mov_b32 s0, 0x21000
	s_nop 0
	v_add_co_u32_e64 v32, s[0:1], s0, v18
	ds_read_b128 v[94:97], v64 offset:24592
	s_nop 0
	v_addc_co_u32_e64 v33, s[0:1], 0, v19, s[0:1]
	s_mov_b32 s0, 0x24000
	s_nop 0
	v_add_co_u32_e64 v38, s[0:1], s0, v18
	s_waitcnt lgkmcnt(9)
	v_fmac_f32_e32 v65, v50, v22
	v_addc_co_u32_e64 v39, s[0:1], 0, v19, s[0:1]
	s_mov_b32 s0, 0x27000
	s_nop 0
	v_add_co_u32_e64 v42, s[0:1], s0, v18
	s_waitcnt lgkmcnt(6)
	v_fmac_f32_e32 v68, v50, v2
	v_addc_co_u32_e64 v43, s[0:1], 0, v19, s[0:1]
	s_mov_b32 s0, 0x2a000
	s_nop 0
	v_add_co_u32_e64 v44, s[0:1], s0, v18
	v_fmac_f32_e32 v65, v51, v23
	v_addc_co_u32_e64 v45, s[0:1], 0, v19, s[0:1]
	s_mov_b32 s0, 0x2d000
	s_nop 0
	v_add_co_u32_e64 v36, s[0:1], s0, v18
	v_fmac_f32_e32 v68, v51, v3
	s_nop 0
	v_addc_co_u32_e64 v37, s[0:1], 0, v19, s[0:1]
	ds_read_b128 v[18:21], v64 offset:24576
	v_fmac_f32_e32 v65, v52, v24
	v_fmac_f32_e32 v68, v52, v4
	v_fmac_f32_e32 v65, v53, v25
	ds_read_b128 v[22:25], v64 offset:8208
	v_fmac_f32_e32 v68, v53, v5
	ds_read_b128 v[2:5], v64 offset:28672
	ds_read_b128 v[98:101], v64 offset:28688
	v_fmac_f32_e32 v0, v50, v72
	v_fmac_f32_e32 v66, v50, v14
	v_fmac_f32_e32 v67, v50, v10
	s_waitcnt lgkmcnt(9)
	v_fmac_f32_e32 v69, v50, v26
	s_waitcnt lgkmcnt(3)
	v_fmac_f32_e32 v70, v50, v18
	s_waitcnt lgkmcnt(1)
	v_fmac_f32_e32 v71, v50, v2
	v_fmac_f32_e32 v0, v51, v73
	v_fmac_f32_e32 v66, v51, v15
	v_fmac_f32_e32 v67, v51, v11
	v_fmac_f32_e32 v69, v51, v27
	v_fmac_f32_e32 v70, v51, v19
	v_fmac_f32_e32 v71, v51, v3
	v_fmac_f32_e32 v0, v52, v74
	v_fmac_f32_e32 v66, v52, v16
	v_fmac_f32_e32 v67, v52, v12
	v_fmac_f32_e32 v69, v52, v28
	v_fmac_f32_e32 v70, v52, v20
	v_fmac_f32_e32 v71, v52, v4
	v_fmac_f32_e32 v0, v53, v75
	v_fmac_f32_e32 v66, v53, v17
	v_fmac_f32_e32 v67, v53, v13
	v_fmac_f32_e32 v69, v53, v29
	v_fmac_f32_e32 v70, v53, v21
	v_fmac_f32_e32 v71, v53, v5
	ds_read_b128 v[50:53], v64 offset:32
	v_mov_b32_e32 v77, v148
	v_mov_b32_e32 v106, v149
	v_mov_b32_e32 v107, v150
	ds_read_b128 v[2:5], v64 offset:48
	v_mov_b32_e32 v76, v151
	v_mov_b32_e32 v75, v152
	v_mov_b32_e32 v74, v153
	v_mov_b32_e32 v72, v154
	v_mov_b32_e32 v73, v155
	ds_read_b128 v[42:45], v64 offset:4128
	ds_read_b128 v[26:29], v64 offset:4144
	v_fmac_f32_e32 v0, v49, v6
	v_fmac_f32_e32 v65, v49, v78
	v_fmac_f32_e32 v66, v49, v22
	v_fmac_f32_e32 v0, v48, v7
	v_fmac_f32_e32 v65, v48, v79
	v_fmac_f32_e32 v66, v48, v23
	v_fmac_f32_e32 v0, v47, v8
	v_fmac_f32_e32 v65, v47, v80
	v_fmac_f32_e32 v66, v47, v24
	ds_read_b128 v[102:105], v64 offset:8224
	ds_read_b128 v[30:33], v64 offset:8240
	v_fmac_f32_e32 v0, v46, v9
	ds_read_b128 v[6:9], v64 offset:12320
	ds_read_b128 v[34:37], v64 offset:12336
	v_fmac_f32_e32 v65, v46, v81
	ds_read_b128 v[10:13], v64 offset:16416
	ds_read_b128 v[38:41], v64 offset:16432
	v_fmac_f32_e32 v66, v46, v25
	ds_read_b128 v[14:17], v64 offset:20512
	ds_read_b128 v[18:21], v64 offset:24608
	ds_read_b128 v[22:25], v64 offset:28704
	v_fmac_f32_e32 v67, v49, v82
	v_fmac_f32_e32 v68, v49, v86
	v_fmac_f32_e32 v69, v49, v90
	v_fmac_f32_e32 v70, v49, v94
	s_waitcnt lgkmcnt(13)
	v_fmac_f32_e32 v71, v49, v98
	v_fmac_f32_e32 v67, v48, v83
	v_fmac_f32_e32 v68, v48, v87
	v_fmac_f32_e32 v69, v48, v91
	v_fmac_f32_e32 v70, v48, v95
	v_fmac_f32_e32 v71, v48, v99
	v_fmac_f32_e32 v67, v47, v84
	v_fmac_f32_e32 v68, v47, v88
	v_fmac_f32_e32 v69, v47, v92
	v_fmac_f32_e32 v70, v47, v96
	v_fmac_f32_e32 v71, v47, v100
	v_fmac_f32_e32 v67, v46, v85
	v_fmac_f32_e32 v68, v46, v89
	v_fmac_f32_e32 v69, v46, v93
	v_fmac_f32_e32 v70, v46, v97
	v_fmac_f32_e32 v71, v46, v101
	ds_read_b128 v[46:49], v64 offset:24624
	s_waitcnt lgkmcnt(13)
	v_fmac_f32_e32 v0, v77, v50
	s_waitcnt lgkmcnt(11)
	v_fmac_f32_e32 v65, v77, v42
	v_fmac_f32_e32 v0, v106, v51
	v_fmac_f32_e32 v65, v106, v43
	v_fmac_f32_e32 v0, v107, v52
	v_fmac_f32_e32 v65, v107, v44
	v_fmac_f32_e32 v0, v76, v53
	v_fmac_f32_e32 v65, v76, v45
	ds_read_b128 v[42:45], v64 offset:20528
	ds_read_b128 v[50:53], v64 offset:28720
	s_waitcnt lgkmcnt(11)
	v_fmac_f32_e32 v66, v77, v102
	s_waitcnt lgkmcnt(9)
	v_fmac_f32_e32 v67, v77, v6
	s_waitcnt lgkmcnt(7)
	v_fmac_f32_e32 v68, v77, v10
	s_waitcnt lgkmcnt(5)
	v_fmac_f32_e32 v69, v77, v14
	s_waitcnt lgkmcnt(4)
	v_fmac_f32_e32 v70, v77, v18
	s_waitcnt lgkmcnt(3)
	v_fmac_f32_e32 v71, v77, v22
	v_fmac_f32_e32 v66, v106, v103
	v_fmac_f32_e32 v67, v106, v7
	v_fmac_f32_e32 v68, v106, v11
	v_fmac_f32_e32 v69, v106, v15
	v_fmac_f32_e32 v70, v106, v19
	v_fmac_f32_e32 v71, v106, v23
	v_fmac_f32_e32 v66, v107, v104
	v_fmac_f32_e32 v67, v107, v8
	v_fmac_f32_e32 v68, v107, v12
	v_fmac_f32_e32 v69, v107, v16
	v_fmac_f32_e32 v70, v107, v20
	v_fmac_f32_e32 v71, v107, v24
	v_fmac_f32_e32 v66, v76, v105
	v_fmac_f32_e32 v67, v76, v9
	v_fmac_f32_e32 v68, v76, v13
	v_fmac_f32_e32 v69, v76, v17
	v_fmac_f32_e32 v70, v76, v21
	v_fmac_f32_e32 v71, v76, v25
	v_fmac_f32_e32 v0, v75, v2
	v_fmac_f32_e32 v65, v75, v26
	v_fmac_f32_e32 v66, v75, v30
	v_fmac_f32_e32 v67, v75, v34
	v_fmac_f32_e32 v68, v75, v38
	s_waitcnt lgkmcnt(1)
	v_fmac_f32_e32 v69, v75, v42
	v_fmac_f32_e32 v70, v75, v46
	s_waitcnt lgkmcnt(0)
	v_fmac_f32_e32 v71, v75, v50
	v_fmac_f32_e32 v0, v74, v3
	v_fmac_f32_e32 v65, v74, v27
	v_fmac_f32_e32 v66, v74, v31
	v_fmac_f32_e32 v67, v74, v35
	v_fmac_f32_e32 v68, v74, v39
	v_fmac_f32_e32 v69, v74, v43
	v_fmac_f32_e32 v70, v74, v47
	v_fmac_f32_e32 v71, v74, v51
	v_fmac_f32_e32 v0, v72, v4
	v_fmac_f32_e32 v65, v72, v28
	v_fmac_f32_e32 v66, v72, v32
	v_fmac_f32_e32 v67, v72, v36
	v_fmac_f32_e32 v68, v72, v40
	v_fmac_f32_e32 v69, v72, v44
	v_fmac_f32_e32 v70, v72, v48
	v_fmac_f32_e32 v71, v72, v52
	v_add_u32_e32 v64, 64, v64
	v_fmac_f32_e32 v0, v73, v5
	v_fmac_f32_e32 v65, v73, v29
	v_fmac_f32_e32 v66, v73, v33
	v_fmac_f32_e32 v67, v73, v37
	v_fmac_f32_e32 v68, v73, v41
	v_fmac_f32_e32 v69, v73, v45
	v_fmac_f32_e32 v70, v73, v49
	v_fmac_f32_e32 v71, v73, v53
	v_lshl_add_u64 v[18:19], v[60:61], 0, s[20:21]
	v_add_co_u32_e64 v20, s[0:1], s29, v18
	ds_read_b128 v[72:75], v64
	ds_read_b128 v[6:9], v64 offset:16
	ds_read_b128 v[22:25], v64 offset:4096
	ds_read_b128 v[14:17], v64 offset:8192
	ds_read_b128 v[10:13], v64 offset:12288
	ds_read_b128 v[2:5], v64 offset:16384
	v_addc_co_u32_e64 v21, s[0:1], 0, v19, s[0:1]
	v_add_co_u32_e64 v26, s[0:1], s5, v18
	s_add_u32 s20, s20, 0x30000
	s_nop 0
	v_addc_co_u32_e64 v27, s[0:1], 0, v19, s[0:1]
	s_mov_b32 s0, 0x9000
	s_nop 0
	v_add_co_u32_e64 v46, s[0:1], s0, v18
	v_mov_b32_e32 v50, v156
	v_mov_b32_e32 v51, v157
	v_mov_b32_e32 v52, v158
	v_addc_co_u32_e64 v47, s[0:1], 0, v19, s[0:1]
	v_add_co_u32_e64 v48, s[0:1], s50, v18
	ds_read_b128 v[26:29], v64 offset:20480
	s_nop 0
	v_addc_co_u32_e64 v49, s[0:1], 0, v19, s[0:1]
	s_mov_b32 s0, 0xf000
	s_nop 0
	v_add_co_u32_e64 v76, s[0:1], s0, v18
	s_addc_u32 s21, s21, 0
	s_nop 0
	v_addc_co_u32_e64 v77, s[0:1], 0, v19, s[0:1]
	s_mov_b32 s0, 0x12000
	s_nop 0
	v_add_co_u32_e64 v78, s[0:1], s0, v18
	s_cmp_eq_u32 s20, 0xc0000
	s_nop 0
	v_addc_co_u32_e64 v79, s[0:1], 0, v19, s[0:1]
	v_mov_b32_e32 v53, v159
	s_nop 0
	v_mov_b32_e32 v49, v160
	s_nop 0
	v_mov_b32_e32 v48, v161
	v_mov_b32_e32 v47, v162
	s_mov_b32 s0, 0x15000
	v_add_co_u32_e64 v80, s[0:1], s0, v18
	ds_read_b128 v[82:85], v64 offset:12304
	ds_read_b128 v[86:89], v64 offset:16400
	v_addc_co_u32_e64 v81, s[0:1], 0, v19, s[0:1]
	v_add_co_u32_e64 v30, s[0:1], s96, v18
	v_mov_b32_e32 v46, v163
	s_nop 0
	v_addc_co_u32_e64 v31, s[0:1], 0, v19, s[0:1]
	s_mov_b32 s0, 0x1b000
	s_nop 0
	v_add_co_u32_e64 v34, s[0:1], s0, v18
	ds_read_b128 v[78:81], v64 offset:4112
	s_nop 0
	v_addc_co_u32_e64 v35, s[0:1], 0, v19, s[0:1]
	s_mov_b32 s0, 0x1e000
	s_nop 0
	v_add_co_u32_e64 v40, s[0:1], s0, v18
	ds_read_b128 v[90:93], v64 offset:20496
	s_nop 0
	v_addc_co_u32_e64 v41, s[0:1], 0, v19, s[0:1]
	s_mov_b32 s0, 0x21000
	s_nop 0
	v_add_co_u32_e64 v32, s[0:1], s0, v18
	ds_read_b128 v[94:97], v64 offset:24592
	s_nop 0
	v_addc_co_u32_e64 v33, s[0:1], 0, v19, s[0:1]
	s_mov_b32 s0, 0x24000
	s_nop 0
	v_add_co_u32_e64 v38, s[0:1], s0, v18
	s_waitcnt lgkmcnt(9)
	v_fmac_f32_e32 v65, v50, v22
	v_addc_co_u32_e64 v39, s[0:1], 0, v19, s[0:1]
	s_mov_b32 s0, 0x27000
	s_nop 0
	v_add_co_u32_e64 v42, s[0:1], s0, v18
	s_waitcnt lgkmcnt(6)
	v_fmac_f32_e32 v68, v50, v2
	v_addc_co_u32_e64 v43, s[0:1], 0, v19, s[0:1]
	s_mov_b32 s0, 0x2a000
	s_nop 0
	v_add_co_u32_e64 v44, s[0:1], s0, v18
	v_fmac_f32_e32 v65, v51, v23
	v_addc_co_u32_e64 v45, s[0:1], 0, v19, s[0:1]
	s_mov_b32 s0, 0x2d000
	s_nop 0
	v_add_co_u32_e64 v36, s[0:1], s0, v18
	v_fmac_f32_e32 v68, v51, v3
	s_nop 0
	v_addc_co_u32_e64 v37, s[0:1], 0, v19, s[0:1]
	ds_read_b128 v[18:21], v64 offset:24576
	v_fmac_f32_e32 v65, v52, v24
	v_fmac_f32_e32 v68, v52, v4
	v_fmac_f32_e32 v65, v53, v25
	ds_read_b128 v[22:25], v64 offset:8208
	v_fmac_f32_e32 v68, v53, v5
	ds_read_b128 v[2:5], v64 offset:28672
	ds_read_b128 v[98:101], v64 offset:28688
	v_fmac_f32_e32 v0, v50, v72
	v_fmac_f32_e32 v66, v50, v14
	v_fmac_f32_e32 v67, v50, v10
	s_waitcnt lgkmcnt(9)
	v_fmac_f32_e32 v69, v50, v26
	s_waitcnt lgkmcnt(3)
	v_fmac_f32_e32 v70, v50, v18
	s_waitcnt lgkmcnt(1)
	v_fmac_f32_e32 v71, v50, v2
	v_fmac_f32_e32 v0, v51, v73
	v_fmac_f32_e32 v66, v51, v15
	v_fmac_f32_e32 v67, v51, v11
	v_fmac_f32_e32 v69, v51, v27
	v_fmac_f32_e32 v70, v51, v19
	v_fmac_f32_e32 v71, v51, v3
	v_fmac_f32_e32 v0, v52, v74
	v_fmac_f32_e32 v66, v52, v16
	v_fmac_f32_e32 v67, v52, v12
	v_fmac_f32_e32 v69, v52, v28
	v_fmac_f32_e32 v70, v52, v20
	v_fmac_f32_e32 v71, v52, v4
	v_fmac_f32_e32 v0, v53, v75
	v_fmac_f32_e32 v66, v53, v17
	v_fmac_f32_e32 v67, v53, v13
	v_fmac_f32_e32 v69, v53, v29
	v_fmac_f32_e32 v70, v53, v21
	v_fmac_f32_e32 v71, v53, v5
	ds_read_b128 v[50:53], v64 offset:32
	v_mov_b32_e32 v77, v164
	v_mov_b32_e32 v106, v165
	v_mov_b32_e32 v107, v166
	ds_read_b128 v[2:5], v64 offset:48
	v_mov_b32_e32 v76, v167
	v_mov_b32_e32 v75, v168
	v_mov_b32_e32 v74, v169
	v_mov_b32_e32 v72, v170
	v_mov_b32_e32 v73, v171
	ds_read_b128 v[42:45], v64 offset:4128
	ds_read_b128 v[26:29], v64 offset:4144
	v_fmac_f32_e32 v0, v49, v6
	v_fmac_f32_e32 v65, v49, v78
	v_fmac_f32_e32 v66, v49, v22
	v_fmac_f32_e32 v0, v48, v7
	v_fmac_f32_e32 v65, v48, v79
	v_fmac_f32_e32 v66, v48, v23
	v_fmac_f32_e32 v0, v47, v8
	v_fmac_f32_e32 v65, v47, v80
	v_fmac_f32_e32 v66, v47, v24
	ds_read_b128 v[102:105], v64 offset:8224
	ds_read_b128 v[30:33], v64 offset:8240
	v_fmac_f32_e32 v0, v46, v9
	ds_read_b128 v[6:9], v64 offset:12320
	ds_read_b128 v[34:37], v64 offset:12336
	v_fmac_f32_e32 v65, v46, v81
	ds_read_b128 v[10:13], v64 offset:16416
	ds_read_b128 v[38:41], v64 offset:16432
	v_fmac_f32_e32 v66, v46, v25
	ds_read_b128 v[14:17], v64 offset:20512
	ds_read_b128 v[18:21], v64 offset:24608
	ds_read_b128 v[22:25], v64 offset:28704
	v_fmac_f32_e32 v67, v49, v82
	v_fmac_f32_e32 v68, v49, v86
	v_fmac_f32_e32 v69, v49, v90
	v_fmac_f32_e32 v70, v49, v94
	s_waitcnt lgkmcnt(13)
	v_fmac_f32_e32 v71, v49, v98
	v_fmac_f32_e32 v67, v48, v83
	v_fmac_f32_e32 v68, v48, v87
	v_fmac_f32_e32 v69, v48, v91
	v_fmac_f32_e32 v70, v48, v95
	v_fmac_f32_e32 v71, v48, v99
	v_fmac_f32_e32 v67, v47, v84
	v_fmac_f32_e32 v68, v47, v88
	v_fmac_f32_e32 v69, v47, v92
	v_fmac_f32_e32 v70, v47, v96
	v_fmac_f32_e32 v71, v47, v100
	v_fmac_f32_e32 v67, v46, v85
	v_fmac_f32_e32 v68, v46, v89
	v_fmac_f32_e32 v69, v46, v93
	v_fmac_f32_e32 v70, v46, v97
	v_fmac_f32_e32 v71, v46, v101
	ds_read_b128 v[46:49], v64 offset:24624
	s_waitcnt lgkmcnt(13)
	v_fmac_f32_e32 v0, v77, v50
	s_waitcnt lgkmcnt(11)
	v_fmac_f32_e32 v65, v77, v42
	v_fmac_f32_e32 v0, v106, v51
	v_fmac_f32_e32 v65, v106, v43
	v_fmac_f32_e32 v0, v107, v52
	v_fmac_f32_e32 v65, v107, v44
	v_fmac_f32_e32 v0, v76, v53
	v_fmac_f32_e32 v65, v76, v45
	ds_read_b128 v[42:45], v64 offset:20528
	ds_read_b128 v[50:53], v64 offset:28720
	s_waitcnt lgkmcnt(11)
	v_fmac_f32_e32 v66, v77, v102
	s_waitcnt lgkmcnt(9)
	v_fmac_f32_e32 v67, v77, v6
	s_waitcnt lgkmcnt(7)
	v_fmac_f32_e32 v68, v77, v10
	s_waitcnt lgkmcnt(5)
	v_fmac_f32_e32 v69, v77, v14
	s_waitcnt lgkmcnt(4)
	v_fmac_f32_e32 v70, v77, v18
	s_waitcnt lgkmcnt(3)
	v_fmac_f32_e32 v71, v77, v22
	v_fmac_f32_e32 v66, v106, v103
	v_fmac_f32_e32 v67, v106, v7
	v_fmac_f32_e32 v68, v106, v11
	v_fmac_f32_e32 v69, v106, v15
	v_fmac_f32_e32 v70, v106, v19
	v_fmac_f32_e32 v71, v106, v23
	v_fmac_f32_e32 v66, v107, v104
	v_fmac_f32_e32 v67, v107, v8
	v_fmac_f32_e32 v68, v107, v12
	v_fmac_f32_e32 v69, v107, v16
	v_fmac_f32_e32 v70, v107, v20
	v_fmac_f32_e32 v71, v107, v24
	v_fmac_f32_e32 v66, v76, v105
	v_fmac_f32_e32 v67, v76, v9
	v_fmac_f32_e32 v68, v76, v13
	v_fmac_f32_e32 v69, v76, v17
	v_fmac_f32_e32 v70, v76, v21
	v_fmac_f32_e32 v71, v76, v25
	v_fmac_f32_e32 v0, v75, v2
	v_fmac_f32_e32 v65, v75, v26
	v_fmac_f32_e32 v66, v75, v30
	v_fmac_f32_e32 v67, v75, v34
	v_fmac_f32_e32 v68, v75, v38
	s_waitcnt lgkmcnt(1)
	v_fmac_f32_e32 v69, v75, v42
	v_fmac_f32_e32 v70, v75, v46
	s_waitcnt lgkmcnt(0)
	v_fmac_f32_e32 v71, v75, v50
	v_fmac_f32_e32 v0, v74, v3
	v_fmac_f32_e32 v65, v74, v27
	v_fmac_f32_e32 v66, v74, v31
	v_fmac_f32_e32 v67, v74, v35
	v_fmac_f32_e32 v68, v74, v39
	v_fmac_f32_e32 v69, v74, v43
	v_fmac_f32_e32 v70, v74, v47
	v_fmac_f32_e32 v71, v74, v51
	v_fmac_f32_e32 v0, v72, v4
	v_fmac_f32_e32 v65, v72, v28
	v_fmac_f32_e32 v66, v72, v32
	v_fmac_f32_e32 v67, v72, v36
	v_fmac_f32_e32 v68, v72, v40
	v_fmac_f32_e32 v69, v72, v44
	v_fmac_f32_e32 v70, v72, v48
	v_fmac_f32_e32 v71, v72, v52
	v_add_u32_e32 v64, 64, v64
	v_fmac_f32_e32 v0, v73, v5
	v_fmac_f32_e32 v65, v73, v29
	v_fmac_f32_e32 v66, v73, v33
	v_fmac_f32_e32 v67, v73, v37
	v_fmac_f32_e32 v68, v73, v41
	v_fmac_f32_e32 v69, v73, v45
	v_fmac_f32_e32 v70, v73, v49
	v_fmac_f32_e32 v71, v73, v53
	v_add_u32_e32 v2, 0x8000, v62
	ds_write2_b32 v2, v0, v65 offset1:32
	ds_write2_b32 v2, v66, v67 offset0:64 offset1:96
	ds_write2_b32 v2, v68, v69 offset0:128 offset1:160
	ds_write2_b32 v2, v70, v71 offset0:192 offset1:224
	s_waitcnt lgkmcnt(0)
	s_barrier
	s_and_saveexec_b64 s[0:1], vcc
	s_cbranch_execz .LBB0_153
	s_mul_i32 s6, s10, 0xc00
	s_add_i32 s6, s6, s18
	v_or_b32_e32 v2, s6, v56
	v_readlane_b32 s52, v253, 15
	v_ashrrev_i32_e32 v3, 31, v2
	v_readlane_b32 s58, v253, 21
	v_readlane_b32 s59, v253, 22
	v_lshl_add_u32 v18, s10, 3, v55
	s_movk_i32 s6, 0xc00
	v_lshl_add_u64 v[2:3], v[2:3], 2, s[58:59]
	global_load_dword v0, v[2:3], off
	ds_read2st64_b32 v[2:3], v63 offset0:128 offset1:132
	ds_read2st64_b32 v[4:5], v63 offset0:136 offset1:140
	ds_read2st64_b32 v[6:7], v63 offset0:144 offset1:148
	ds_read2st64_b32 v[8:9], v63 offset0:152 offset1:156
	ds_read2st64_b32 v[10:11], v63 offset0:160 offset1:164
	ds_read2st64_b32 v[12:13], v63 offset0:168 offset1:172
	ds_read2st64_b32 v[14:15], v63 offset0:176 offset1:180
	ds_read2st64_b32 v[16:17], v63 offset0:184 offset1:188
	s_waitcnt lgkmcnt(7)
	v_add_f32_e32 v2, 0, v2
	v_add_f32_e32 v2, v2, v3
	s_waitcnt lgkmcnt(6)
	v_add_f32_e32 v2, v2, v4
	v_add_f32_e32 v2, v2, v5
	s_waitcnt lgkmcnt(5)
	v_add_f32_e32 v2, v2, v6
	v_add_f32_e32 v2, v2, v7
	s_waitcnt lgkmcnt(4)
	v_add_f32_e32 v2, v2, v8
	v_add_f32_e32 v2, v2, v9
	s_waitcnt lgkmcnt(3)
	v_add_f32_e32 v2, v2, v10
	v_add_f32_e32 v2, v2, v11
	s_waitcnt lgkmcnt(2)
	v_add_f32_e32 v2, v2, v12
	v_add_f32_e32 v2, v2, v13
	v_mul_lo_u32 v18, v18, s6
	s_waitcnt lgkmcnt(1)
	v_add_f32_e32 v2, v2, v14
	v_add_u32_e32 v18, s18, v18
	v_add_f32_e32 v2, v2, v15
	v_or_b32_e32 v18, v18, v56
	s_waitcnt lgkmcnt(0)
	v_add_f32_e32 v2, v2, v16
	v_readlane_b32 s61, v253, 24
	v_ashrrev_i32_e32 v19, 31, v18
	v_add_f32_e32 v2, v2, v17
	s_movk_i32 s61, 0xfff
	v_readlane_b32 s53, v253, 16
	v_readlane_b32 s54, v253, 17
	v_readlane_b32 s55, v253, 18
	v_readlane_b32 s56, v253, 19
	v_readlane_b32 s57, v253, 20
	v_readlane_b32 s60, v253, 23
	v_readlane_b32 s62, v253, 25
	v_readlane_b32 s63, v253, 26
	v_readlane_b32 s64, v253, 27
	v_readlane_b32 s65, v253, 28
	v_readlane_b32 s66, v253, 29
	v_readlane_b32 s67, v253, 30
	s_waitcnt vmcnt(0)
	v_add_f32_e32 v0, v2, v0
	v_lshl_add_u64 v[2:3], v[18:19], 2, s[22:23]
	global_store_dword v[2:3], v0, off
	s_branch .LBB0_153
